# thin_gemm<1,4>/<2,4>: epilogue gate / T loads issued at the piece start (before the operand loads) instead of after the reduction barrier; on top of v27
# baseline (speedup 1.0000x reference)
.LBB0_918:
	s_and_b32 s12, s1, 0xffffffe0
	s_and_b32 s20, s0, 0x3e0
	v_add_u32_e32 v25, s12, v21
	v_mov_b64_e32 v[60:61], s[6:7]
	v_add_u32_e32 v62, s20, v22
	v_ashrrev_i32_e32 v63, 31, v62
	v_mad_i64_i32 v[66:67], vcc, v25, s22, v[60:61]
	v_lshl_add_u64 v[66:67], v[62:63], 1, v[66:67]
	v_add_co_u32_e32 v60, vcc, s97, v66
	s_nop 1
	v_addc_co_u32_e32 v61, vcc, 0, v67, vcc
	global_load_dword v64, v[60:61], off offset:2048
	v_or_b32_e32 v0, s20, v20
	v_mad_i64_i32 v[46:47], s[12:13], v25, s22, v[16:17]
	v_lshlrev_b32_e32 v138, 10, v0
	v_lshl_add_u64 v[42:43], v[18:19], 0, v[138:139]
	global_load_dwordx4 v[0:3], v[46:47], off
	global_load_dwordx4 v[26:29], v[46:47], off offset:32
	global_load_dwordx4 v[30:33], v[46:47], off offset:64
	global_load_dwordx4 v[4:7], v[42:43], off
	global_load_dwordx4 v[34:37], v[42:43], off offset:32
	global_load_dwordx4 v[38:41], v[42:43], off offset:64
	s_nop 0
	global_load_dwordx4 v[42:45], v[42:43], off offset:96
	s_add_i32 s1, s1, s96
	s_add_i32 s0, s0, s15
	s_cmpk_lt_i32 s1, 0x100
	s_waitcnt vmcnt(3)
	v_mfma_f32_32x32x16_bf16 v[0:15], v[4:7], v[0:3], 0
	s_waitcnt vmcnt(2)
	v_mfma_f32_32x32x16_bf16 v[0:15], v[34:37], v[26:29], v[0:15]
	global_load_dwordx4 v[26:29], v[46:47], off offset:96
	v_mov_b64_e32 v[34:35], s[6:7]
	v_add_u32_e32 v36, s20, v22
	v_ashrrev_i32_e32 v37, 31, v36
	s_waitcnt vmcnt(2)
	v_mfma_f32_32x32x16_bf16 v[0:15], v[38:41], v[30:33], v[0:15]
	v_mad_i64_i32 v[30:31], s[12:13], v25, s22, v[34:35]
	v_lshl_add_u64 v[30:31], v[36:37], 1, v[30:31]
	v_add_co_u32_e32 v32, vcc, s97, v30
	s_nop 1
	v_addc_co_u32_e32 v33, vcc, 0, v31, vcc
	s_waitcnt vmcnt(0)
	v_mfma_f32_32x32x16_bf16 v[0:15], v[42:45], v[26:29], v[0:15]
	s_nop 11
	ds_write2st64_b32 v23, v0, v1 offset1:1
	ds_write2st64_b32 v23, v2, v3 offset0:2 offset1:3
	ds_write2st64_b32 v23, v4, v5 offset0:4 offset1:5
	ds_write2st64_b32 v23, v6, v7 offset0:6 offset1:7
	ds_write2st64_b32 v23, v8, v9 offset0:8 offset1:9
	ds_write2st64_b32 v23, v10, v11 offset0:10 offset1:11
	ds_write2st64_b32 v23, v12, v13 offset0:12 offset1:13
	ds_write2st64_b32 v23, v14, v15 offset0:14 offset1:15
	s_waitcnt lgkmcnt(0)
	s_barrier
	ds_read2st64_b32 v[0:1], v24 offset1:1
	ds_read2st64_b32 v[2:3], v24 offset0:16 offset1:17
	ds_read2st64_b32 v[4:5], v24 offset0:32 offset1:33
	ds_read2st64_b32 v[6:7], v24 offset0:48 offset1:49
	ds_read2st64_b32 v[8:9], v24 offset0:64 offset1:65
	ds_read2st64_b32 v[10:11], v24 offset0:80 offset1:81
	ds_read2st64_b32 v[12:13], v24 offset0:96 offset1:97
	ds_read2st64_b32 v[14:15], v24 offset0:112 offset1:113
	s_waitcnt lgkmcnt(7)
	v_add_f32_e32 v0, 0, v0
	v_add_f32_e32 v1, 0, v1
	s_waitcnt lgkmcnt(6)
	v_add_f32_e32 v0, v0, v2
	v_add_f32_e32 v1, v1, v3
	s_waitcnt lgkmcnt(5)
	v_add_f32_e32 v0, v0, v4
	v_add_f32_e32 v1, v1, v5
	s_waitcnt lgkmcnt(4)
	v_add_f32_e32 v0, v0, v6
	v_add_f32_e32 v1, v1, v7
	s_waitcnt lgkmcnt(3)
	v_add_f32_e32 v0, v0, v8
	v_add_f32_e32 v1, v1, v9
	s_waitcnt lgkmcnt(2)
	v_add_f32_e32 v0, v0, v10
	v_add_f32_e32 v1, v1, v11
	s_waitcnt lgkmcnt(1)
	v_add_f32_e32 v0, v0, v12
	v_add_f32_e32 v1, v1, v13
	s_waitcnt lgkmcnt(0)
	v_add_f32_e32 v0, v0, v14
	v_add_f32_e32 v1, v1, v15
	s_waitcnt vmcnt(0)
	v_lshlrev_b32_e32 v2, 16, v64
	v_and_b32_e32 v3, 0xffff0000, v64
	v_fma_f32 v0, v0, v2, 0
	v_fma_f32 v1, v1, v3, 0
	v_cvt_pk_bf16_f32 v0, v0, v1
	global_store_dword v[30:31], v0, off offset:1024
	s_barrier
	s_cbranch_scc1 .LBB0_918

.LBB0_1027:
	s_and_b32 s12, s1, 0xffffffe0
	s_and_b32 s20, s0, 0x3e0
	v_add_u32_e32 v25, s12, v21
	v_mov_b64_e32 v[60:61], s[6:7]
	v_add_u32_e32 v62, s20, v22
	v_ashrrev_i32_e32 v63, 31, v62
	v_mad_i64_i32 v[66:67], vcc, v25, s22, v[60:61]
	v_lshl_add_u64 v[66:67], v[62:63], 1, v[66:67]
	v_add_co_u32_e32 v60, vcc, s8, v66
	s_nop 1
	v_addc_co_u32_e32 v61, vcc, 0, v67, vcc
	global_load_dword v64, v[60:61], off
	global_load_dword v65, v[66:67], off offset:1024
	v_or_b32_e32 v0, s20, v20
	v_mad_i64_i32 v[46:47], s[12:13], v25, s22, v[16:17]
	v_lshlrev_b32_e32 v138, 10, v0
	v_lshl_add_u64 v[42:43], v[18:19], 0, v[138:139]
	global_load_dwordx4 v[0:3], v[46:47], off
	global_load_dwordx4 v[26:29], v[46:47], off offset:32
	global_load_dwordx4 v[30:33], v[46:47], off offset:64
	global_load_dwordx4 v[4:7], v[42:43], off
	global_load_dwordx4 v[34:37], v[42:43], off offset:32
	global_load_dwordx4 v[38:41], v[42:43], off offset:64
	s_nop 0
	global_load_dwordx4 v[42:45], v[42:43], off offset:96
	s_add_i32 s1, s1, s96
	s_add_i32 s0, s0, s15
	s_cmpk_lt_i32 s1, 0x100
	s_waitcnt vmcnt(3)
	v_mfma_f32_32x32x16_bf16 v[0:15], v[4:7], v[0:3], 0
	s_waitcnt vmcnt(2)
	v_mfma_f32_32x32x16_bf16 v[0:15], v[34:37], v[26:29], v[0:15]
	global_load_dwordx4 v[26:29], v[46:47], off offset:96
	v_mov_b64_e32 v[34:35], s[6:7]
	v_add_u32_e32 v36, s20, v22
	v_ashrrev_i32_e32 v37, 31, v36
	s_waitcnt vmcnt(2)
	v_mfma_f32_32x32x16_bf16 v[0:15], v[38:41], v[30:33], v[0:15]
	v_mad_i64_i32 v[30:31], s[12:13], v25, s22, v[34:35]
	v_lshl_add_u64 v[30:31], v[36:37], 1, v[30:31]
	v_add_co_u32_e32 v32, vcc, s8, v30
	s_nop 1
	v_addc_co_u32_e32 v33, vcc, 0, v31, vcc
	s_waitcnt vmcnt(0)
	v_mfma_f32_32x32x16_bf16 v[0:15], v[42:45], v[26:29], v[0:15]
	s_nop 11
	ds_write2st64_b32 v23, v0, v1 offset1:1
	ds_write2st64_b32 v23, v2, v3 offset0:2 offset1:3
	ds_write2st64_b32 v23, v4, v5 offset0:4 offset1:5
	ds_write2st64_b32 v23, v6, v7 offset0:6 offset1:7
	ds_write2st64_b32 v23, v8, v9 offset0:8 offset1:9
	ds_write2st64_b32 v23, v10, v11 offset0:10 offset1:11
	ds_write2st64_b32 v23, v12, v13 offset0:12 offset1:13
	ds_write2st64_b32 v23, v14, v15 offset0:14 offset1:15
	s_waitcnt lgkmcnt(0)
	s_barrier
	ds_read2st64_b32 v[0:1], v24 offset1:1
	ds_read2st64_b32 v[2:3], v24 offset0:16 offset1:17
	ds_read2st64_b32 v[4:5], v24 offset0:32 offset1:33
	ds_read2st64_b32 v[6:7], v24 offset0:48 offset1:49
	ds_read2st64_b32 v[8:9], v24 offset0:64 offset1:65
	ds_read2st64_b32 v[10:11], v24 offset0:80 offset1:81
	ds_read2st64_b32 v[12:13], v24 offset0:96 offset1:97
	ds_read2st64_b32 v[14:15], v24 offset0:112 offset1:113
	s_waitcnt lgkmcnt(7)
	v_add_f32_e32 v0, 0, v0
	v_add_f32_e32 v1, 0, v1
	s_waitcnt lgkmcnt(6)
	v_add_f32_e32 v0, v0, v2
	v_add_f32_e32 v1, v1, v3
	s_waitcnt lgkmcnt(5)
	v_add_f32_e32 v0, v0, v4
	v_add_f32_e32 v1, v1, v5
	s_waitcnt lgkmcnt(4)
	v_add_f32_e32 v0, v0, v6
	v_add_f32_e32 v1, v1, v7
	s_waitcnt lgkmcnt(3)
	v_add_f32_e32 v0, v0, v8
	v_add_f32_e32 v1, v1, v9
	s_waitcnt lgkmcnt(2)
	v_add_f32_e32 v0, v0, v10
	v_add_f32_e32 v1, v1, v11
	s_waitcnt lgkmcnt(1)
	v_add_f32_e32 v0, v0, v12
	v_add_f32_e32 v1, v1, v13
	s_waitcnt lgkmcnt(0)
	v_add_f32_e32 v0, v0, v14
	v_add_f32_e32 v1, v1, v15
	s_waitcnt vmcnt(1)
	v_lshlrev_b32_e32 v2, 16, v64
	v_and_b32_e32 v3, 0xffff0000, v64
	s_waitcnt vmcnt(0)
	v_lshlrev_b32_e32 v4, 16, v65
	v_and_b32_e32 v5, 0xffff0000, v65
	v_fmac_f32_e32 v4, v0, v2
	v_fmac_f32_e32 v5, v1, v3
	v_cvt_pk_bf16_f32 v0, v4, v5
	global_store_dword v[30:31], v0, off offset:1024
	s_barrier
	s_cbranch_scc1 .LBB0_1027
